# grid barrier: non-leader L1 invalidate issued before the release poll + non-leaders poll the cross-XCD generation directly; 4-phase K-loop in gate/up GEMM
# speedup vs baseline: 1.0165x; 1.0165x over previous
.LBB0_27:
	s_or_b64 exec, exec, s[2:3]
	v_cvt_f32_u32_e32 v6, v4
	s_waitcnt vmcnt(0)
	v_readfirstlane_b32 s2, v5
	v_sub_u32_e32 v5, 0, v4
	v_rcp_iflag_f32_e32 v6, v6
	v_add_u32_e32 v7, s2, v3
	v_mul_f32_e32 v6, 0x4f7ffffe, v6
	v_cvt_u32_f32_e32 v6, v6
	v_mul_lo_u32 v3, v5, v6
	v_mul_hi_u32 v3, v6, v3
	v_add_u32_e32 v3, v6, v3
	v_mul_hi_u32 v3, v7, v3
	v_mul_lo_u32 v5, v3, v4
	v_sub_u32_e32 v5, v7, v5
	v_add_u32_e32 v6, 1, v3
	v_cmp_ge_u32_e32 vcc, v5, v4
	s_nop 1
	v_cndmask_b32_e32 v3, v3, v6, vcc
	v_sub_u32_e32 v6, v5, v4
	v_cndmask_b32_e32 v5, v5, v6, vcc
	v_add_u32_e32 v6, 1, v3
	v_cmp_ge_u32_e32 vcc, v5, v4
	v_add_u32_e32 v5, 1, v7
	s_nop 0
	v_cndmask_b32_e32 v3, v3, v6, vcc
	v_mul_lo_u32 v6, v4, v3
	v_add_u32_e32 v4, v6, v4
	v_cmp_ne_u32_e32 vcc, v5, v4
	s_and_saveexec_b64 s[2:3], vcc
	s_xor_b64 s[2:3], exec, s[2:3]
	s_cbranch_execz .LBB0_41
	v_readlane_b32 s4, v251, 0
	v_readlane_b32 s5, v251, 1
	s_waitcnt lgkmcnt(0)
	s_nop 3
	buffer_inv sc1
	global_load_dword v2, v191, s[4:5] sc1
	s_waitcnt vmcnt(0)
	v_cmp_eq_u32_e32 vcc, v2, v3
	s_and_saveexec_b64 s[4:5], vcc
	s_cbranch_execz .LBB0_40
	s_mov_b32 s16, 1
	s_mov_b64 s[6:7], 0
	s_branch .LBB0_31

.LBB0_33:
	v_readlane_b32 s10, v251, 0
	v_readlane_b32 s11, v251, 1
	s_add_i32 s16, s16, 1
	s_mov_b64 s[12:13], -1
	s_nop 2
	global_load_dword v2, v191, s[10:11] sc1
	s_waitcnt vmcnt(0)
	v_cmp_ne_u32_e32 vcc, v2, v3
	s_orn2_b64 s[10:11], vcc, exec
	s_branch .LBB0_30

.LBB0_40:
	s_or_b64 exec, exec, s[4:5]
	s_waitcnt vmcnt(0)
	s_waitcnt vmcnt(0)
